# prologue: the 14 full-tile group-A matrices go through the streamlined converter, hipcc's convert_mats keeps the four padded ones; otherwise v59
# speedup vs baseline: 1.0016x; 1.0016x over previous
; #define LAS __attribute__((address_space(3)))
;     __device__ __forceinline__ void ids() { lane = fresh_lane(); tid = wave * 64 + lane; }
; __device__ __forceinline__ void convert_mats(Frame& F, int m_lo, int m_hi, int gw, int NGW) {
;     LAS float* scr = (LAS float*)(F.lds + F.wave * 16384);
;     int it = gw, base = 0;
;     for (int mi = m_lo; mi < m_hi; ++mi) {
;         const MatI mt = kMats[mi]; const int cnt = (mt.Kp / 64) * (mt.Np / 64);
;         const float* src = in_ptr(F, mt.in_idx) + mt.src_off; const float* gain = mt.gain_idx >= 0 ? in_ptr(F, mt.gain_idx) + mt.gain_off : nullptr; bf16* dst = (bf16*)((unsigned char*)in_ptr(F, T_WS) + mt.dst_off);
;         while (it < base + cnt) {
;             f32x4 va[2][8], vb[2][8];
;             const int lim = base + cnt, i1 = it + NGW;
;             conv_load(src, mt.K, mt.N, mt.Np, it - base, F.lane, va);
; __device__ __forceinline__ void p_prologue(Frame& F) {
;     F.ids();
;     unsigned char* const ws_ = (unsigned char*)in_ptr(F, T_WS);
;     const int gw = F.vcu * NWAVES + F.wave, NGW = F.G * NWAVES;
;     convert_mats(F, 0, 22, gw, NGW);
.LBB0_11:
	s_or_b64 exec, exec, s[4:5]
	s_load_dwordx2 s[56:57], s[0:1], 0x128
	s_waitcnt lgkmcnt(0)
	s_cmp_lt_i32 s56, 1
	s_cselect_b64 s[0:1], -1, 0
	s_cmp_gt_i32 s57, 0
	s_cselect_b64 s[4:5], -1, 0
	s_and_b64 s[0:1], s[0:1], s[4:5]
	s_andn2_b64 vcc, exec, s[0:1]
	s_cbranch_vccnz .LBB0_189
	s_mov_b32 s33, s96
	s_mov_b32 s3, s52
	v_mbcnt_lo_u32_b32 v182, -1, 0
	v_mbcnt_hi_u32_b32 v182, -1, v182
	v_lshrrev_b32_e32 v183, 3, v182
	v_and_b32_e32 v184, 7, v182
	s_lshl_b32 s4, s80, 14
	v_mul_u32_u24_e32 v0, 132, v183
	v_lshl_add_u32 v0, v184, 4, v0
	v_add_u32_e32 v172, s4, v0
	v_add_u32_e32 v173, 0x420, v172
	v_add_u32_e32 v174, 0x840, v172
	v_add_u32_e32 v175, 0xc60, v172
	v_add_u32_e32 v176, 0x1080, v172
	v_add_u32_e32 v177, 0x14a0, v172
	v_add_u32_e32 v178, 0x18c0, v172
	v_add_u32_e32 v179, 0x1ce0, v172
	v_mul_u32_u24_e32 v0, 0x420, v184
	v_lshl_add_u32 v0, v183, 2, v0
	v_add_u32_e32 v180, s4, v0
	v_lshlrev_b32_e32 v181, 2, v183
	s_lshl_b32 s20, s33, 3
	s_add_u32 s20, s20, s80
	s_lshl_b32 s21, s3, 3
	s_mov_b32 s22, 0
	s_add_i32 s4, 0, 0x20520
	v_mov_b32_e32 v0, s4
	ds_read_b64 v[2:3], v0
	s_waitcnt lgkmcnt(0)
	s_nop 0
	v_readfirstlane_b32 s58, v2
	v_readfirstlane_b32 s59, v3
	s_add_u32 s23, s22, 0x2400
	s_cmp_ge_u32 s20, s23
	s_cbranch_scc1 .Lcvp_m0_done
	s_add_i32 s4, 0, 0x20418
	v_mov_b32_e32 v0, s4
	ds_read_b64 v[2:3], v0
	s_waitcnt lgkmcnt(0)
	s_nop 0
	v_readfirstlane_b32 s24, v2
	v_readfirstlane_b32 s25, v3
	s_add_u32 s24, s24, 0x0
	s_addc_u32 s25, s25, 0
	s_add_i32 s4, 0, 0x20410
	v_mov_b32_e32 v0, s4
	ds_read_b64 v[2:3], v0
	s_waitcnt lgkmcnt(0)
	s_nop 0
	v_readfirstlane_b32 s26, v2
	v_readfirstlane_b32 s27, v3
	s_add_u32 s26, s26, 0x0
	s_addc_u32 s27, s27, 0
	s_add_u32 s28, s58, 0x100000
	s_addc_u32 s29, s59, 0
	s_mov_b32 s30, 0x12000
	s_mov_b32 s31, 0x1000
	s_mov_b32 s34, 0xe38e39
	s_mov_b32 s35, 288
	s_mov_b32 s36, 0
	v_mul_lo_u32 v0, v183, s30
	v_lshl_add_u32 v160, v184, 4, v0
	v_add_u32_e32 v161, 0x90000, v160
	v_add_u32_e32 v162, 0x120000, v160
	v_add_u32_e32 v163, 0x1b0000, v160
	v_add_u32_e32 v164, 0x240000, v160
	v_add_u32_e32 v165, 0x2d0000, v160
	v_add_u32_e32 v166, 0x360000, v160
	v_add_u32_e32 v167, 0x3f0000, v160
	v_mul_lo_u32 v0, v183, s31
	v_lshl_add_u32 v168, v184, 4, v0
	v_add_u32_e32 v169, 0x8000, v168
	v_add_u32_e32 v170, 0x10000, v168
	v_add_u32_e32 v171, 0x18000, v168

; #define LAS __attribute__((address_space(3)))
; __device__ __forceinline__ void convert_mats(Frame& F, int m_lo, int m_hi, int gw, int NGW) {
;     LAS float* scr = (LAS float*)(F.lds + F.wave * 16384);
;     int it = gw, base = 0;
;     for (int mi = m_lo; mi < m_hi; ++mi) {
;         const MatI mt = kMats[mi]; const int cnt = (mt.Kp / 64) * (mt.Np / 64);
;         const float* src = in_ptr(F, mt.in_idx) + mt.src_off; const float* gain = mt.gain_idx >= 0 ? in_ptr(F, mt.gain_idx) + mt.gain_off : nullptr; bf16* dst = (bf16*)((unsigned char*)in_ptr(F, T_WS) + mt.dst_off);
;         while (it < base + cnt) {
;             f32x4 va[2][8], vb[2][8];
;             const int lim = base + cnt, i1 = it + NGW;
;             conv_load(src, mt.K, mt.N, mt.Np, it - base, F.lane, va);
;             if (i1 < lim) conv_load(src, mt.K, mt.N, mt.Np, i1 - base, F.lane, vb);
;             conv_proc(va, gain, mt.K, mt.Kp, mt.Np, mt.ilv, dst, scr, it - base, F.lane);
;             if (i1 < lim) conv_proc(vb, gain, mt.K, mt.Kp, mt.Np, mt.ilv, dst, scr, i1 - base, F.lane);
;             it = (i1 < lim) ? i1 + NGW : i1;
.Lcvp_m0_done:
	s_mov_b32 s22, s23
	s_add_u32 s23, s22, 0x400
	s_cmp_ge_u32 s20, s23
	s_cbranch_scc1 .Lcvp_m1_done
	s_add_i32 s4, 0, 0x20420
	v_mov_b32_e32 v0, s4
	ds_read_b64 v[2:3], v0
	s_waitcnt lgkmcnt(0)
	s_nop 0
	v_readfirstlane_b32 s24, v2
	v_readfirstlane_b32 s25, v3
	s_add_u32 s24, s24, 0x0
	s_addc_u32 s25, s25, 0
	s_add_u32 s28, s58, 0x9100000
	s_addc_u32 s29, s59, 0
	s_mov_b32 s30, 0x2000
	s_mov_b32 s31, 0x1000
	s_mov_b32 s34, 0x8000000
	s_mov_b32 s35, 32
	s_mov_b32 s36, 0
	v_mul_lo_u32 v0, v183, s30
	v_lshl_add_u32 v160, v184, 4, v0
	v_add_u32_e32 v161, 0x10000, v160
	v_add_u32_e32 v162, 0x20000, v160
	v_add_u32_e32 v163, 0x30000, v160
	v_add_u32_e32 v164, 0x40000, v160
	v_add_u32_e32 v165, 0x50000, v160
	v_add_u32_e32 v166, 0x60000, v160
	v_add_u32_e32 v167, 0x70000, v160
	v_mul_lo_u32 v0, v183, s31
	v_lshl_add_u32 v168, v184, 4, v0
	v_add_u32_e32 v169, 0x8000, v168
	v_add_u32_e32 v170, 0x10000, v168
	v_add_u32_e32 v171, 0x18000, v168

; #define LAS __attribute__((address_space(3)))
; __device__ __forceinline__ void convert_mats(Frame& F, int m_lo, int m_hi, int gw, int NGW) {
;     LAS float* scr = (LAS float*)(F.lds + F.wave * 16384);
;     int it = gw, base = 0;
;     for (int mi = m_lo; mi < m_hi; ++mi) {
;         const MatI mt = kMats[mi]; const int cnt = (mt.Kp / 64) * (mt.Np / 64);
;         const float* src = in_ptr(F, mt.in_idx) + mt.src_off; const float* gain = mt.gain_idx >= 0 ? in_ptr(F, mt.gain_idx) + mt.gain_off : nullptr; bf16* dst = (bf16*)((unsigned char*)in_ptr(F, T_WS) + mt.dst_off);
;         while (it < base + cnt) {
;             f32x4 va[2][8], vb[2][8];
;             const int lim = base + cnt, i1 = it + NGW;
;             conv_load(src, mt.K, mt.N, mt.Np, it - base, F.lane, va);
;             if (i1 < lim) conv_load(src, mt.K, mt.N, mt.Np, i1 - base, F.lane, vb);
;             conv_proc(va, gain, mt.K, mt.Kp, mt.Np, mt.ilv, dst, scr, it - base, F.lane);
;             if (i1 < lim) conv_proc(vb, gain, mt.K, mt.Kp, mt.Np, mt.ilv, dst, scr, i1 - base, F.lane);
;             it = (i1 < lim) ? i1 + NGW : i1;
.Lcvp_m1_done:
	s_mov_b32 s22, s23
	s_add_u32 s23, s22, 0x400
	s_cmp_ge_u32 s20, s23
	s_cbranch_scc1 .Lcvp_m2_done
	s_add_i32 s4, 0, 0x20438
	v_mov_b32_e32 v0, s4
	ds_read_b64 v[2:3], v0
	s_waitcnt lgkmcnt(0)
	s_nop 0
	v_readfirstlane_b32 s24, v2
	v_readfirstlane_b32 s25, v3
	s_add_u32 s24, s24, 0x0
	s_addc_u32 s25, s25, 0
	s_add_u32 s28, s58, 0xa100000
	s_addc_u32 s29, s59, 0
	s_mov_b32 s30, 0x2000
	s_mov_b32 s31, 0x1000
	s_mov_b32 s34, 0x8000000
	s_mov_b32 s35, 32
	s_mov_b32 s36, 0
	v_mul_lo_u32 v0, v183, s30
	v_lshl_add_u32 v160, v184, 4, v0
	v_add_u32_e32 v161, 0x10000, v160
	v_add_u32_e32 v162, 0x20000, v160
	v_add_u32_e32 v163, 0x30000, v160
	v_add_u32_e32 v164, 0x40000, v160
	v_add_u32_e32 v165, 0x50000, v160
	v_add_u32_e32 v166, 0x60000, v160
	v_add_u32_e32 v167, 0x70000, v160
	v_mul_lo_u32 v0, v183, s31
	v_lshl_add_u32 v168, v184, 4, v0
	v_add_u32_e32 v169, 0x8000, v168
	v_add_u32_e32 v170, 0x10000, v168
	v_add_u32_e32 v171, 0x18000, v168

; #define LAS __attribute__((address_space(3)))
; __device__ __forceinline__ void convert_mats(Frame& F, int m_lo, int m_hi, int gw, int NGW) {
;     LAS float* scr = (LAS float*)(F.lds + F.wave * 16384);
;     int it = gw, base = 0;
;     for (int mi = m_lo; mi < m_hi; ++mi) {
;         const MatI mt = kMats[mi]; const int cnt = (mt.Kp / 64) * (mt.Np / 64);
;         const float* src = in_ptr(F, mt.in_idx) + mt.src_off; const float* gain = mt.gain_idx >= 0 ? in_ptr(F, mt.gain_idx) + mt.gain_off : nullptr; bf16* dst = (bf16*)((unsigned char*)in_ptr(F, T_WS) + mt.dst_off);
;         while (it < base + cnt) {
;             f32x4 va[2][8], vb[2][8];
;             const int lim = base + cnt, i1 = it + NGW;
;             conv_load(src, mt.K, mt.N, mt.Np, it - base, F.lane, va);
;             if (i1 < lim) conv_load(src, mt.K, mt.N, mt.Np, i1 - base, F.lane, vb);
;             conv_proc(va, gain, mt.K, mt.Kp, mt.Np, mt.ilv, dst, scr, it - base, F.lane);
;             if (i1 < lim) conv_proc(vb, gain, mt.K, mt.Kp, mt.Np, mt.ilv, dst, scr, i1 - base, F.lane);
;             it = (i1 < lim) ? i1 + NGW : i1;
.Lcvp_m2_done:
	s_mov_b32 s22, s23
	s_add_u32 s23, s22, 0x400
	s_cmp_ge_u32 s20, s23
	s_cbranch_scc1 .Lcvp_m3_done
	s_add_i32 s4, 0, 0x20438
	v_mov_b32_e32 v0, s4
	ds_read_b64 v[2:3], v0
	s_waitcnt lgkmcnt(0)
	s_nop 0
	v_readfirstlane_b32 s24, v2
	v_readfirstlane_b32 s25, v3
	s_add_u32 s24, s24, 0x1000000
	s_addc_u32 s25, s25, 0
	s_add_u32 s28, s58, 0xa900000
	s_addc_u32 s29, s59, 0
	s_mov_b32 s30, 0x2000
	s_mov_b32 s31, 0x1000
	s_mov_b32 s34, 0x8000000
	s_mov_b32 s35, 32
	s_mov_b32 s36, 0
	v_mul_lo_u32 v0, v183, s30
	v_lshl_add_u32 v160, v184, 4, v0
	v_add_u32_e32 v161, 0x10000, v160
	v_add_u32_e32 v162, 0x20000, v160
	v_add_u32_e32 v163, 0x30000, v160
	v_add_u32_e32 v164, 0x40000, v160
	v_add_u32_e32 v165, 0x50000, v160
	v_add_u32_e32 v166, 0x60000, v160
	v_add_u32_e32 v167, 0x70000, v160
	v_mul_lo_u32 v0, v183, s31
	v_lshl_add_u32 v168, v184, 4, v0
	v_add_u32_e32 v169, 0x8000, v168
	v_add_u32_e32 v170, 0x10000, v168
	v_add_u32_e32 v171, 0x18000, v168

; #define LAS __attribute__((address_space(3)))
; __device__ __forceinline__ void convert_mats(Frame& F, int m_lo, int m_hi, int gw, int NGW) {
;     LAS float* scr = (LAS float*)(F.lds + F.wave * 16384);
;     int it = gw, base = 0;
;     for (int mi = m_lo; mi < m_hi; ++mi) {
;         const MatI mt = kMats[mi]; const int cnt = (mt.Kp / 64) * (mt.Np / 64);
;         const float* src = in_ptr(F, mt.in_idx) + mt.src_off; const float* gain = mt.gain_idx >= 0 ? in_ptr(F, mt.gain_idx) + mt.gain_off : nullptr; bf16* dst = (bf16*)((unsigned char*)in_ptr(F, T_WS) + mt.dst_off);
;         while (it < base + cnt) {
;             f32x4 va[2][8], vb[2][8];
;             const int lim = base + cnt, i1 = it + NGW;
;             conv_load(src, mt.K, mt.N, mt.Np, it - base, F.lane, va);
;             if (i1 < lim) conv_load(src, mt.K, mt.N, mt.Np, i1 - base, F.lane, vb);
;             conv_proc(va, gain, mt.K, mt.Kp, mt.Np, mt.ilv, dst, scr, it - base, F.lane);
;             if (i1 < lim) conv_proc(vb, gain, mt.K, mt.Kp, mt.Np, mt.ilv, dst, scr, i1 - base, F.lane);
;             it = (i1 < lim) ? i1 + NGW : i1;
.Lcvp_m3_done:
	s_mov_b32 s22, s23
	s_add_u32 s23, s22, 0x400
	s_cmp_ge_u32 s20, s23
	s_cbranch_scc1 .Lcvp_m4_done
	s_add_i32 s4, 0, 0x20438
	v_mov_b32_e32 v0, s4
	ds_read_b64 v[2:3], v0
	s_waitcnt lgkmcnt(0)
	s_nop 0
	v_readfirstlane_b32 s24, v2
	v_readfirstlane_b32 s25, v3
	s_add_u32 s24, s24, 0x2000000
	s_addc_u32 s25, s25, 0
	s_add_u32 s28, s58, 0xb100000
	s_addc_u32 s29, s59, 0
	s_mov_b32 s30, 0x2000
	s_mov_b32 s31, 0x1000
	s_mov_b32 s34, 0x8000000
	s_mov_b32 s35, 32
	s_mov_b32 s36, 0
	v_mul_lo_u32 v0, v183, s30
	v_lshl_add_u32 v160, v184, 4, v0
	v_add_u32_e32 v161, 0x10000, v160
	v_add_u32_e32 v162, 0x20000, v160
	v_add_u32_e32 v163, 0x30000, v160
	v_add_u32_e32 v164, 0x40000, v160
	v_add_u32_e32 v165, 0x50000, v160
	v_add_u32_e32 v166, 0x60000, v160
	v_add_u32_e32 v167, 0x70000, v160
	v_mul_lo_u32 v0, v183, s31
	v_lshl_add_u32 v168, v184, 4, v0
	v_add_u32_e32 v169, 0x8000, v168
	v_add_u32_e32 v170, 0x10000, v168
	v_add_u32_e32 v171, 0x18000, v168

; #define LAS __attribute__((address_space(3)))
; __device__ __forceinline__ void convert_mats(Frame& F, int m_lo, int m_hi, int gw, int NGW) {
;     LAS float* scr = (LAS float*)(F.lds + F.wave * 16384);
;     int it = gw, base = 0;
;     for (int mi = m_lo; mi < m_hi; ++mi) {
;         const MatI mt = kMats[mi]; const int cnt = (mt.Kp / 64) * (mt.Np / 64);
;         const float* src = in_ptr(F, mt.in_idx) + mt.src_off; const float* gain = mt.gain_idx >= 0 ? in_ptr(F, mt.gain_idx) + mt.gain_off : nullptr; bf16* dst = (bf16*)((unsigned char*)in_ptr(F, T_WS) + mt.dst_off);
;         while (it < base + cnt) {
;             f32x4 va[2][8], vb[2][8];
;             const int lim = base + cnt, i1 = it + NGW;
;             conv_load(src, mt.K, mt.N, mt.Np, it - base, F.lane, va);
;             if (i1 < lim) conv_load(src, mt.K, mt.N, mt.Np, i1 - base, F.lane, vb);
;             conv_proc(va, gain, mt.K, mt.Kp, mt.Np, mt.ilv, dst, scr, it - base, F.lane);
;             if (i1 < lim) conv_proc(vb, gain, mt.K, mt.Kp, mt.Np, mt.ilv, dst, scr, i1 - base, F.lane);
;             it = (i1 < lim) ? i1 + NGW : i1;
.Lcvp_m4_done:
	s_mov_b32 s22, s23
	s_add_u32 s23, s22, 0x80
	s_cmp_ge_u32 s20, s23
	s_cbranch_scc1 .Lcvp_m7_done
	s_add_i32 s4, 0, 0x20470
	v_mov_b32_e32 v0, s4
	ds_read_b64 v[2:3], v0
	s_waitcnt lgkmcnt(0)
	s_nop 0
	v_readfirstlane_b32 s24, v2
	v_readfirstlane_b32 s25, v3
	s_add_u32 s24, s24, 0x0
	s_addc_u32 s25, s25, 0
	s_add_u32 s28, s58, 0xbb00000
	s_addc_u32 s29, s59, 0
	s_mov_b32 s30, 0x400
	s_mov_b32 s31, 0x1000
	s_mov_b32 s34, 0x40000000
	s_mov_b32 s35, 4
	s_mov_b32 s36, 0
	v_mul_lo_u32 v0, v183, s30
	v_lshl_add_u32 v160, v184, 4, v0
	v_add_u32_e32 v161, 0x2000, v160
	v_add_u32_e32 v162, 0x4000, v160
	v_add_u32_e32 v163, 0x6000, v160
	v_add_u32_e32 v164, 0x8000, v160
	v_add_u32_e32 v165, 0xa000, v160
	v_add_u32_e32 v166, 0xc000, v160
	v_add_u32_e32 v167, 0xe000, v160
	v_mul_lo_u32 v0, v183, s31
	v_lshl_add_u32 v168, v184, 4, v0
	v_add_u32_e32 v169, 0x8000, v168
	v_add_u32_e32 v170, 0x10000, v168
	v_add_u32_e32 v171, 0x18000, v168

; #define LAS __attribute__((address_space(3)))
; __device__ __forceinline__ void convert_mats(Frame& F, int m_lo, int m_hi, int gw, int NGW) {
;     LAS float* scr = (LAS float*)(F.lds + F.wave * 16384);
;     int it = gw, base = 0;
;     for (int mi = m_lo; mi < m_hi; ++mi) {
;         const MatI mt = kMats[mi]; const int cnt = (mt.Kp / 64) * (mt.Np / 64);
;         const float* src = in_ptr(F, mt.in_idx) + mt.src_off; const float* gain = mt.gain_idx >= 0 ? in_ptr(F, mt.gain_idx) + mt.gain_off : nullptr; bf16* dst = (bf16*)((unsigned char*)in_ptr(F, T_WS) + mt.dst_off);
;         while (it < base + cnt) {
;             f32x4 va[2][8], vb[2][8];
;             const int lim = base + cnt, i1 = it + NGW;
;             conv_load(src, mt.K, mt.N, mt.Np, it - base, F.lane, va);
;             if (i1 < lim) conv_load(src, mt.K, mt.N, mt.Np, i1 - base, F.lane, vb);
;             conv_proc(va, gain, mt.K, mt.Kp, mt.Np, mt.ilv, dst, scr, it - base, F.lane);
;             if (i1 < lim) conv_proc(vb, gain, mt.K, mt.Kp, mt.Np, mt.ilv, dst, scr, i1 - base, F.lane);
;             it = (i1 < lim) ? i1 + NGW : i1;
.Lcvp_m7_done:
	s_mov_b32 s22, s23
	s_add_u32 s23, s22, 0x80
	s_cmp_ge_u32 s20, s23
	s_cbranch_scc1 .Lcvp_m10_done
	s_add_i32 s4, 0, 0x20478
	v_mov_b32_e32 v0, s4
	ds_read_b64 v[2:3], v0
	s_waitcnt lgkmcnt(0)
	s_nop 0
	v_readfirstlane_b32 s24, v2
	v_readfirstlane_b32 s25, v3
	s_add_u32 s24, s24, 0x0
	s_addc_u32 s25, s25, 0
	s_add_u32 s28, s58, 0xbe00000
	s_addc_u32 s29, s59, 0
	s_mov_b32 s30, 0x2000
	s_mov_b32 s31, 0x200
	s_mov_b32 s34, 0x8000000
	s_mov_b32 s35, 32
	s_mov_b32 s36, 0
	v_mul_lo_u32 v0, v183, s30
	v_lshl_add_u32 v160, v184, 4, v0
	v_add_u32_e32 v161, 0x10000, v160
	v_add_u32_e32 v162, 0x20000, v160
	v_add_u32_e32 v163, 0x30000, v160
	v_add_u32_e32 v164, 0x40000, v160
	v_add_u32_e32 v165, 0x50000, v160
	v_add_u32_e32 v166, 0x60000, v160
	v_add_u32_e32 v167, 0x70000, v160
	v_mul_lo_u32 v0, v183, s31
	v_lshl_add_u32 v168, v184, 4, v0
	v_add_u32_e32 v169, 0x1000, v168
	v_add_u32_e32 v170, 0x2000, v168
	v_add_u32_e32 v171, 0x3000, v168

; #define LAS __attribute__((address_space(3)))
; __device__ __forceinline__ void convert_mats(Frame& F, int m_lo, int m_hi, int gw, int NGW) {
;     LAS float* scr = (LAS float*)(F.lds + F.wave * 16384);
;     int it = gw, base = 0;
;     for (int mi = m_lo; mi < m_hi; ++mi) {
;         const MatI mt = kMats[mi]; const int cnt = (mt.Kp / 64) * (mt.Np / 64);
;         const float* src = in_ptr(F, mt.in_idx) + mt.src_off; const float* gain = mt.gain_idx >= 0 ? in_ptr(F, mt.gain_idx) + mt.gain_off : nullptr; bf16* dst = (bf16*)((unsigned char*)in_ptr(F, T_WS) + mt.dst_off);
;         while (it < base + cnt) {
;             f32x4 va[2][8], vb[2][8];
;             const int lim = base + cnt, i1 = it + NGW;
;             conv_load(src, mt.K, mt.N, mt.Np, it - base, F.lane, va);
;             if (i1 < lim) conv_load(src, mt.K, mt.N, mt.Np, i1 - base, F.lane, vb);
;             conv_proc(va, gain, mt.K, mt.Kp, mt.Np, mt.ilv, dst, scr, it - base, F.lane);
;             if (i1 < lim) conv_proc(vb, gain, mt.K, mt.Kp, mt.Np, mt.ilv, dst, scr, i1 - base, F.lane);
;             it = (i1 < lim) ? i1 + NGW : i1;
.Lcvp_m10_done:
	s_mov_b32 s22, s23
	s_add_u32 s23, s22, 0x1600
	s_cmp_ge_u32 s20, s23
	s_cbranch_scc1 .Lcvp_m12_done
	s_add_i32 s4, 0, 0x204d8
	v_mov_b32_e32 v0, s4
	ds_read_b64 v[2:3], v0
	s_waitcnt lgkmcnt(0)
	s_nop 0
	v_readfirstlane_b32 s24, v2
	v_readfirstlane_b32 s25, v3
	s_add_u32 s24, s24, 0x0
	s_addc_u32 s25, s25, 0
	s_add_i32 s4, 0, 0x204d0
	v_mov_b32_e32 v0, s4
	ds_read_b64 v[2:3], v0
	s_waitcnt lgkmcnt(0)
	s_nop 0
	v_readfirstlane_b32 s26, v2
	v_readfirstlane_b32 s27, v3
	s_add_u32 s26, s26, 0x0
	s_addc_u32 s27, s27, 0
	s_add_u32 s28, s58, 0xe700000
	s_addc_u32 s29, s59, 0
	s_mov_b32 s30, 0xb000
	s_mov_b32 s31, 0x1000
	s_mov_b32 s34, 0x1745d18
	s_mov_b32 s35, 176
	s_mov_b32 s36, 5632
	v_mul_lo_u32 v0, v183, s30
	v_lshl_add_u32 v160, v184, 4, v0
	v_add_u32_e32 v161, 0x58000, v160
	v_add_u32_e32 v162, 0xb0000, v160
	v_add_u32_e32 v163, 0x108000, v160
	v_add_u32_e32 v164, 0x160000, v160
	v_add_u32_e32 v165, 0x1b8000, v160
	v_add_u32_e32 v166, 0x210000, v160
	v_add_u32_e32 v167, 0x268000, v160
	v_mul_lo_u32 v0, v183, s31
	v_lshl_add_u32 v168, v184, 4, v0
	v_add_u32_e32 v169, 0x8000, v168
	v_add_u32_e32 v170, 0x10000, v168
	v_add_u32_e32 v171, 0x18000, v168

; #define LAS __attribute__((address_space(3)))
; __device__ __forceinline__ void convert_mats(Frame& F, int m_lo, int m_hi, int gw, int NGW) {
;     LAS float* scr = (LAS float*)(F.lds + F.wave * 16384);
;     int it = gw, base = 0;
;     for (int mi = m_lo; mi < m_hi; ++mi) {
;         const MatI mt = kMats[mi]; const int cnt = (mt.Kp / 64) * (mt.Np / 64);
;         const float* src = in_ptr(F, mt.in_idx) + mt.src_off; const float* gain = mt.gain_idx >= 0 ? in_ptr(F, mt.gain_idx) + mt.gain_off : nullptr; bf16* dst = (bf16*)((unsigned char*)in_ptr(F, T_WS) + mt.dst_off);
;         while (it < base + cnt) {
;             f32x4 va[2][8], vb[2][8];
;             const int lim = base + cnt, i1 = it + NGW;
;             conv_load(src, mt.K, mt.N, mt.Np, it - base, F.lane, va);
;             if (i1 < lim) conv_load(src, mt.K, mt.N, mt.Np, i1 - base, F.lane, vb);
;             conv_proc(va, gain, mt.K, mt.Kp, mt.Np, mt.ilv, dst, scr, it - base, F.lane);
;             if (i1 < lim) conv_proc(vb, gain, mt.K, mt.Kp, mt.Np, mt.ilv, dst, scr, i1 - base, F.lane);
;             it = (i1 < lim) ? i1 + NGW : i1;
.Lcvp_m12_done:
	s_mov_b32 s22, s23
	s_add_u32 s23, s22, 0xb00
	s_cmp_ge_u32 s20, s23
	s_cbranch_scc1 .Lcvp_m14_done
	s_add_i32 s4, 0, 0x204f0
	v_mov_b32_e32 v0, s4
	ds_read_b64 v[2:3], v0
	s_waitcnt lgkmcnt(0)
	s_nop 0
	v_readfirstlane_b32 s24, v2
	v_readfirstlane_b32 s25, v3
	s_add_u32 s24, s24, 0x0
	s_addc_u32 s25, s25, 0
	s_add_u32 s28, s58, 0x19700000
	s_addc_u32 s29, s59, 0
	s_mov_b32 s30, 0x2000
	s_mov_b32 s31, 0x2c00
	s_mov_b32 s34, 0x8000000
	s_mov_b32 s35, 32
	s_mov_b32 s36, 0
	v_mul_lo_u32 v0, v183, s30
	v_lshl_add_u32 v160, v184, 4, v0
	v_add_u32_e32 v161, 0x10000, v160
	v_add_u32_e32 v162, 0x20000, v160
	v_add_u32_e32 v163, 0x30000, v160
	v_add_u32_e32 v164, 0x40000, v160
	v_add_u32_e32 v165, 0x50000, v160
	v_add_u32_e32 v166, 0x60000, v160
	v_add_u32_e32 v167, 0x70000, v160
	v_mul_lo_u32 v0, v183, s31
	v_lshl_add_u32 v168, v184, 4, v0
	v_add_u32_e32 v169, 0x16000, v168
	v_add_u32_e32 v170, 0x2c000, v168
	v_add_u32_e32 v171, 0x42000, v168

; #define LAS __attribute__((address_space(3)))
; __device__ __forceinline__ void convert_mats(Frame& F, int m_lo, int m_hi, int gw, int NGW) {
;     LAS float* scr = (LAS float*)(F.lds + F.wave * 16384);
;     int it = gw, base = 0;
;     for (int mi = m_lo; mi < m_hi; ++mi) {
;         const MatI mt = kMats[mi]; const int cnt = (mt.Kp / 64) * (mt.Np / 64);
;         const float* src = in_ptr(F, mt.in_idx) + mt.src_off; const float* gain = mt.gain_idx >= 0 ? in_ptr(F, mt.gain_idx) + mt.gain_off : nullptr; bf16* dst = (bf16*)((unsigned char*)in_ptr(F, T_WS) + mt.dst_off);
;         while (it < base + cnt) {
;             f32x4 va[2][8], vb[2][8];
;             const int lim = base + cnt, i1 = it + NGW;
;             conv_load(src, mt.K, mt.N, mt.Np, it - base, F.lane, va);
;             if (i1 < lim) conv_load(src, mt.K, mt.N, mt.Np, i1 - base, F.lane, vb);
;             conv_proc(va, gain, mt.K, mt.Kp, mt.Np, mt.ilv, dst, scr, it - base, F.lane);
;             if (i1 < lim) conv_proc(vb, gain, mt.K, mt.Kp, mt.Np, mt.ilv, dst, scr, i1 - base, F.lane);
;             it = (i1 < lim) ? i1 + NGW : i1;
.Lcvp_m14_done:
	s_mov_b32 s22, s23
	s_add_u32 s23, s22, 0x400
	s_cmp_ge_u32 s20, s23
	s_cbranch_scc1 .Lcvp_m16_done
	s_add_i32 s4, 0, 0x20508
	v_mov_b32_e32 v0, s4
	ds_read_b64 v[2:3], v0
	s_waitcnt lgkmcnt(0)
	s_nop 0
	v_readfirstlane_b32 s24, v2
	v_readfirstlane_b32 s25, v3
	s_add_u32 s24, s24, 0x0
	s_addc_u32 s25, s25, 0
	s_add_i32 s4, 0, 0x20500
	v_mov_b32_e32 v0, s4
	ds_read_b64 v[2:3], v0
	s_waitcnt lgkmcnt(0)
	s_nop 0
	v_readfirstlane_b32 s26, v2
	v_readfirstlane_b32 s27, v3
	s_add_u32 s26, s26, 0x0
	s_addc_u32 s27, s27, 0
	s_add_u32 s28, s58, 0x1ef00000
	s_addc_u32 s29, s59, 0
	s_mov_b32 s30, 0x2000
	s_mov_b32 s31, 0x1000
	s_mov_b32 s34, 0x8000000
	s_mov_b32 s35, 32
	s_mov_b32 s36, 0
	v_mul_lo_u32 v0, v183, s30
	v_lshl_add_u32 v160, v184, 4, v0
	v_add_u32_e32 v161, 0x10000, v160
	v_add_u32_e32 v162, 0x20000, v160
	v_add_u32_e32 v163, 0x30000, v160
	v_add_u32_e32 v164, 0x40000, v160
	v_add_u32_e32 v165, 0x50000, v160
	v_add_u32_e32 v166, 0x60000, v160
	v_add_u32_e32 v167, 0x70000, v160
	v_mul_lo_u32 v0, v183, s31
	v_lshl_add_u32 v168, v184, 4, v0
	v_add_u32_e32 v169, 0x8000, v168
	v_add_u32_e32 v170, 0x10000, v168
	v_add_u32_e32 v171, 0x18000, v168

; #define LAS __attribute__((address_space(3)))
; __device__ __forceinline__ void convert_mats(Frame& F, int m_lo, int m_hi, int gw, int NGW) {
;     LAS float* scr = (LAS float*)(F.lds + F.wave * 16384);
;     int it = gw, base = 0;
;     for (int mi = m_lo; mi < m_hi; ++mi) {
;         const MatI mt = kMats[mi]; const int cnt = (mt.Kp / 64) * (mt.Np / 64);
;         const float* src = in_ptr(F, mt.in_idx) + mt.src_off; const float* gain = mt.gain_idx >= 0 ? in_ptr(F, mt.gain_idx) + mt.gain_off : nullptr; bf16* dst = (bf16*)((unsigned char*)in_ptr(F, T_WS) + mt.dst_off);
;         while (it < base + cnt) {
;             f32x4 va[2][8], vb[2][8];
;             const int lim = base + cnt, i1 = it + NGW;
;             conv_load(src, mt.K, mt.N, mt.Np, it - base, F.lane, va);
;             if (i1 < lim) conv_load(src, mt.K, mt.N, mt.Np, i1 - base, F.lane, vb);
;             conv_proc(va, gain, mt.K, mt.Kp, mt.Np, mt.ilv, dst, scr, it - base, F.lane);
;             if (i1 < lim) conv_proc(vb, gain, mt.K, mt.Kp, mt.Np, mt.ilv, dst, scr, i1 - base, F.lane);
;             it = (i1 < lim) ? i1 + NGW : i1;
.Lcvp_m16_done:
	s_mov_b32 s22, s23
	s_add_u32 s23, s22, 0x80
	s_cmp_ge_u32 s20, s23
	s_cbranch_scc1 .Lcvp_m18_done
	s_add_i32 s4, 0, 0x204f8
	v_mov_b32_e32 v0, s4
	ds_read_b64 v[2:3], v0
	s_waitcnt lgkmcnt(0)
	s_nop 0
	v_readfirstlane_b32 s24, v2
	v_readfirstlane_b32 s25, v3
	s_add_u32 s24, s24, 0x0
	s_addc_u32 s25, s25, 0
	s_add_u32 s28, s58, 0x20f00000
	s_addc_u32 s29, s59, 0
	s_mov_b32 s30, 0x2000
	s_mov_b32 s31, 0x200
	s_mov_b32 s34, 0x8000000
	s_mov_b32 s35, 32
	s_mov_b32 s36, 0
	v_mul_lo_u32 v0, v183, s30
	v_lshl_add_u32 v160, v184, 4, v0
	v_add_u32_e32 v161, 0x10000, v160
	v_add_u32_e32 v162, 0x20000, v160
	v_add_u32_e32 v163, 0x30000, v160
	v_add_u32_e32 v164, 0x40000, v160
	v_add_u32_e32 v165, 0x50000, v160
	v_add_u32_e32 v166, 0x60000, v160
	v_add_u32_e32 v167, 0x70000, v160
	v_mul_lo_u32 v0, v183, s31
	v_lshl_add_u32 v168, v184, 4, v0
	v_add_u32_e32 v169, 0x1000, v168
	v_add_u32_e32 v170, 0x2000, v168
	v_add_u32_e32 v171, 0x3000, v168

; #define LAS __attribute__((address_space(3)))
; __device__ __forceinline__ void convert_mats(Frame& F, int m_lo, int m_hi, int gw, int NGW) {
;     LAS float* scr = (LAS float*)(F.lds + F.wave * 16384);
;     int it = gw, base = 0;
;     for (int mi = m_lo; mi < m_hi; ++mi) {
;         const MatI mt = kMats[mi]; const int cnt = (mt.Kp / 64) * (mt.Np / 64);
;         const float* src = in_ptr(F, mt.in_idx) + mt.src_off; const float* gain = mt.gain_idx >= 0 ? in_ptr(F, mt.gain_idx) + mt.gain_off : nullptr; bf16* dst = (bf16*)((unsigned char*)in_ptr(F, T_WS) + mt.dst_off);
;         while (it < base + cnt) {
;             f32x4 va[2][8], vb[2][8];
;             const int lim = base + cnt, i1 = it + NGW;
;             conv_load(src, mt.K, mt.N, mt.Np, it - base, F.lane, va);
;             if (i1 < lim) conv_load(src, mt.K, mt.N, mt.Np, i1 - base, F.lane, vb);
;             conv_proc(va, gain, mt.K, mt.Kp, mt.Np, mt.ilv, dst, scr, it - base, F.lane);
;             if (i1 < lim) conv_proc(vb, gain, mt.K, mt.Kp, mt.Np, mt.ilv, dst, scr, i1 - base, F.lane);
;             it = (i1 < lim) ? i1 + NGW : i1;
.Lcvp_m18_done:
	s_mov_b32 s22, s23
	s_add_u32 s23, s22, 0x80
	s_cmp_ge_u32 s20, s23
	s_cbranch_scc1 .Lcvp_m19_done
	s_add_i32 s4, 0, 0x204f8
	v_mov_b32_e32 v0, s4
	ds_read_b64 v[2:3], v0
	s_waitcnt lgkmcnt(0)
	s_nop 0
	v_readfirstlane_b32 s24, v2
	v_readfirstlane_b32 s25, v3
	s_add_u32 s24, s24, 0x200000
	s_addc_u32 s25, s25, 0
	s_add_u32 s28, s58, 0x21000000
	s_addc_u32 s29, s59, 0
	s_mov_b32 s30, 0x2000
	s_mov_b32 s31, 0x200
	s_mov_b32 s34, 0x8000000
	s_mov_b32 s35, 32
	s_mov_b32 s36, 0
	v_mul_lo_u32 v0, v183, s30
	v_lshl_add_u32 v160, v184, 4, v0
	v_add_u32_e32 v161, 0x10000, v160
	v_add_u32_e32 v162, 0x20000, v160
	v_add_u32_e32 v163, 0x30000, v160
	v_add_u32_e32 v164, 0x40000, v160
	v_add_u32_e32 v165, 0x50000, v160
	v_add_u32_e32 v166, 0x60000, v160
	v_add_u32_e32 v167, 0x70000, v160
	v_mul_lo_u32 v0, v183, s31
	v_lshl_add_u32 v168, v184, 4, v0
	v_add_u32_e32 v169, 0x1000, v168
	v_add_u32_e32 v170, 0x2000, v168
	v_add_u32_e32 v171, 0x3000, v168

; #define LAS __attribute__((address_space(3)))
; __device__ __forceinline__ void convert_mats(Frame& F, int m_lo, int m_hi, int gw, int NGW) {
;     LAS float* scr = (LAS float*)(F.lds + F.wave * 16384);
;     int it = gw, base = 0;
;     for (int mi = m_lo; mi < m_hi; ++mi) {
;         const MatI mt = kMats[mi]; const int cnt = (mt.Kp / 64) * (mt.Np / 64);
;         const float* src = in_ptr(F, mt.in_idx) + mt.src_off; const float* gain = mt.gain_idx >= 0 ? in_ptr(F, mt.gain_idx) + mt.gain_off : nullptr; bf16* dst = (bf16*)((unsigned char*)in_ptr(F, T_WS) + mt.dst_off);
;         while (it < base + cnt) {
;             f32x4 va[2][8], vb[2][8];
;             const int lim = base + cnt, i1 = it + NGW;
;             conv_load(src, mt.K, mt.N, mt.Np, it - base, F.lane, va);
;             if (i1 < lim) conv_load(src, mt.K, mt.N, mt.Np, i1 - base, F.lane, vb);
;             conv_proc(va, gain, mt.K, mt.Kp, mt.Np, mt.ilv, dst, scr, it - base, F.lane);
;             if (i1 < lim) conv_proc(vb, gain, mt.K, mt.Kp, mt.Np, mt.ilv, dst, scr, i1 - base, F.lane);
;             it = (i1 < lim) ? i1 + NGW : i1;
.Lcvp_m19_done:
	s_mov_b32 s22, s23
	s_add_u32 s23, s22, 0x80
	s_cmp_ge_u32 s20, s23
	s_cbranch_scc1 .Lcvp_m20_done
	s_add_i32 s4, 0, 0x204f8
	v_mov_b32_e32 v0, s4
	ds_read_b64 v[2:3], v0
	s_waitcnt lgkmcnt(0)
	s_nop 0
	v_readfirstlane_b32 s24, v2
	v_readfirstlane_b32 s25, v3
	s_add_u32 s24, s24, 0x400000
	s_addc_u32 s25, s25, 0
	s_add_u32 s28, s58, 0x21100000
	s_addc_u32 s29, s59, 0
	s_mov_b32 s30, 0x2000
	s_mov_b32 s31, 0x200
	s_mov_b32 s34, 0x8000000
	s_mov_b32 s35, 32
	s_mov_b32 s36, 0
	v_mul_lo_u32 v0, v183, s30
	v_lshl_add_u32 v160, v184, 4, v0
	v_add_u32_e32 v161, 0x10000, v160
	v_add_u32_e32 v162, 0x20000, v160
	v_add_u32_e32 v163, 0x30000, v160
	v_add_u32_e32 v164, 0x40000, v160
	v_add_u32_e32 v165, 0x50000, v160
	v_add_u32_e32 v166, 0x60000, v160
	v_add_u32_e32 v167, 0x70000, v160
	v_mul_lo_u32 v0, v183, s31
	v_lshl_add_u32 v168, v184, 4, v0
	v_add_u32_e32 v169, 0x1000, v168
	v_add_u32_e32 v170, 0x2000, v168
	v_add_u32_e32 v171, 0x3000, v168

; #define LAS __attribute__((address_space(3)))
; __device__ __forceinline__ void convert_mats(Frame& F, int m_lo, int m_hi, int gw, int NGW) {
;     LAS float* scr = (LAS float*)(F.lds + F.wave * 16384);
;     int it = gw, base = 0;
;     for (int mi = m_lo; mi < m_hi; ++mi) {
;         const MatI mt = kMats[mi]; const int cnt = (mt.Kp / 64) * (mt.Np / 64);
;         const float* src = in_ptr(F, mt.in_idx) + mt.src_off; const float* gain = mt.gain_idx >= 0 ? in_ptr(F, mt.gain_idx) + mt.gain_off : nullptr; bf16* dst = (bf16*)((unsigned char*)in_ptr(F, T_WS) + mt.dst_off);
;         while (it < base + cnt) {
;             f32x4 va[2][8], vb[2][8];
;             const int lim = base + cnt, i1 = it + NGW;
;             conv_load(src, mt.K, mt.N, mt.Np, it - base, F.lane, va);
;             if (i1 < lim) conv_load(src, mt.K, mt.N, mt.Np, i1 - base, F.lane, vb);
;             conv_proc(va, gain, mt.K, mt.Kp, mt.Np, mt.ilv, dst, scr, it - base, F.lane);
;             if (i1 < lim) conv_proc(vb, gain, mt.K, mt.Kp, mt.Np, mt.ilv, dst, scr, i1 - base, F.lane);
;             it = (i1 < lim) ? i1 + NGW : i1;
.Lcvp_m20_done:
	s_mov_b32 s22, s23
	s_add_u32 s23, s22, 0x80
	s_cmp_ge_u32 s20, s23
	s_cbranch_scc1 .Lcvp_m21_done
	s_add_i32 s4, 0, 0x204f8
	v_mov_b32_e32 v0, s4
	ds_read_b64 v[2:3], v0
	s_waitcnt lgkmcnt(0)
	s_nop 0
	v_readfirstlane_b32 s24, v2
	v_readfirstlane_b32 s25, v3
	s_add_u32 s24, s24, 0x600000
	s_addc_u32 s25, s25, 0
	s_add_u32 s28, s58, 0x21200000
	s_addc_u32 s29, s59, 0
	s_mov_b32 s30, 0x2000
	s_mov_b32 s31, 0x200
	s_mov_b32 s34, 0x8000000
	s_mov_b32 s35, 32
	s_mov_b32 s36, 0
	v_mul_lo_u32 v0, v183, s30
	v_lshl_add_u32 v160, v184, 4, v0
	v_add_u32_e32 v161, 0x10000, v160
	v_add_u32_e32 v162, 0x20000, v160
	v_add_u32_e32 v163, 0x30000, v160
	v_add_u32_e32 v164, 0x40000, v160
	v_add_u32_e32 v165, 0x50000, v160
	v_add_u32_e32 v166, 0x60000, v160
	v_add_u32_e32 v167, 0x70000, v160
	v_mul_lo_u32 v0, v183, s31
	v_lshl_add_u32 v168, v184, 4, v0
	v_add_u32_e32 v169, 0x1000, v168
	v_add_u32_e32 v170, 0x2000, v168
	v_add_u32_e32 v171, 0x3000, v168

; #define LAS __attribute__((address_space(3)))
; __device__ __forceinline__ void convert_mats(Frame& F, int m_lo, int m_hi, int gw, int NGW) {
;     LAS float* scr = (LAS float*)(F.lds + F.wave * 16384);
;     int it = gw, base = 0;
;     for (int mi = m_lo; mi < m_hi; ++mi) {
;         const MatI mt = kMats[mi]; const int cnt = (mt.Kp / 64) * (mt.Np / 64);
;         const float* src = in_ptr(F, mt.in_idx) + mt.src_off; const float* gain = mt.gain_idx >= 0 ? in_ptr(F, mt.gain_idx) + mt.gain_off : nullptr; bf16* dst = (bf16*)((unsigned char*)in_ptr(F, T_WS) + mt.dst_off);
;         while (it < base + cnt) {
;             f32x4 va[2][8], vb[2][8];
;             const int lim = base + cnt, i1 = it + NGW;
.Lcvp_m21_done:
	s_mov_b32 s22, s23
	s_waitcnt vmcnt(0)
	s_add_i32 s3, 0, 0x20520
	v_mov_b32_e32 v0, s3
	v_mbcnt_lo_u32_b32 v132, -1, 0
	v_mbcnt_hi_u32_b32 v132, -1, v132
	ds_read_b64 v[0:1], v0
	s_lshl_b32 s0, s96, 3
	s_add_i32 s44, s0, s80
	s_lshl_b32 s0, s80, 14
	v_ashrrev_i32_e32 v133, 3, v132
	s_waitcnt lgkmcnt(0)
	v_readfirstlane_b32 s38, v0
	v_lshlrev_b32_e32 v0, 2, v132
	v_and_b32_e32 v143, 28, v0
	v_and_b32_e32 v0, 7, v132
	s_add_i32 s0, s0, 0
	v_mul_u32_u24_e32 v3, 0x420, v0
	v_lshlrev_b32_e32 v4, 2, v133
	v_readfirstlane_b32 s39, v1
	v_lshl_add_u32 v1, v0, 4, s0
	v_add3_u32 v145, s0, v3, v4
	s_movk_i32 s0, 0x84
	v_lshlrev_b32_e32 v2, 3, v0
	v_mul_lo_u32 v3, v133, s0
	s_mov_b32 s49, 0
	s_lshl_b32 s46, s52, 3
	v_mov_b32_e32 v0, 0
	v_add_u32_e32 v147, 8, v133
	v_add_u32_e32 v149, 16, v133
	v_add_u32_e32 v151, 24, v133
	v_lshlrev_b32_e32 v134, 1, v2
	v_add_u32_e32 v153, v1, v3
	s_mov_b32 s20, s44
	s_mov_b32 s34, 0
	s_mov_b32 s33, 0
	s_branch .LBB0_14
.Lpro_skip:
	s_add_i32 s33, s33, 1
	s_cmp_lg_u32 s33, 22
	s_cbranch_scc1 .LBB0_14
	s_branch .LBB0_127

; __device__ __forceinline__ void convert_mats(Frame& F, int m_lo, int m_hi, int gw, int NGW) {
;     ...
;     for (int mi = m_lo; mi < m_hi; ++mi) {
;         const MatI mt = kMats[mi]; const int cnt = (mt.Kp / 64) * (mt.Np / 64);
;         const float* src = in_ptr(F, mt.in_idx) + mt.src_off; const float* gain = mt.gain_idx >= 0 ? in_ptr(F, mt.gain_idx) + mt.gain_off : nullptr; bf16* dst = (bf16*)((unsigned char*)in_ptr(F, T_WS) + mt.dst_off);
;         while (it < base + cnt) {
.LBB0_14:
	s_lshl_b32 s4, 1, s33
	s_and_b32 s4, s4, 0x3ffc9f
	s_cmp_lg_u32 s4, 0
	s_cbranch_scc1 .Lpro_skip
	s_mul_i32 s8, s33, 56
	s_getpc_b64 s[0:1]
	s_add_u32 s0, s0, _ZL5kMats@rel32@lo+4
	s_addc_u32 s1, s1, _ZL5kMats@rel32@hi+12
	s_mul_hi_u32 s9, s33, 56
	s_add_u32 s10, s0, s8
	s_addc_u32 s11, s1, s9
	s_getpc_b64 s[0:1]
	s_add_u32 s0, s0, _ZL5kMats@rel32@lo+12
	s_addc_u32 s1, s1, _ZL5kMats@rel32@hi+20
	s_add_u32 s0, s0, s8
	s_addc_u32 s1, s1, s9
	s_load_dword s12, s[10:11], 0x0
	s_getpc_b64 s[4:5]
	s_add_u32 s4, s4, _ZL5kMats@rel32@lo+28
	s_addc_u32 s5, s5, _ZL5kMats@rel32@hi+36
	s_add_u32 s6, s4, s8
	s_addc_u32 s7, s5, s9
	s_getpc_b64 s[4:5]
	s_add_u32 s4, s4, _ZL5kMats@rel32@lo+36
	s_addc_u32 s5, s5, _ZL5kMats@rel32@hi+44
	s_add_u32 s8, s4, s8
	s_addc_u32 s9, s5, s9
	s_waitcnt lgkmcnt(0)
	s_lshl_b32 s4, s12, 3
	s_add_i32 s4, s4, 0
	s_add_i32 s4, s4, 0x20400
	v_mov_b32_e32 v1, s4
	ds_read_b64 v[2:3], v1
	s_lshl_b64 s[4:5], 1, s33
	s_and_b32 s48, s4, 0xad433001
	s_cmp_eq_u64 s[48:49], 0
	s_mov_b64 s[50:51], 0
	s_waitcnt lgkmcnt(0)
	v_readfirstlane_b32 s12, v2
	v_readfirstlane_b32 s13, v3
	s_cbranch_scc1 .LBB0_16
	s_load_dwordx2 s[10:11], s[10:11], 0x10
	s_waitcnt lgkmcnt(0)
	s_lshl_b32 s5, s10, 3
	s_add_i32 s5, s5, 0
	s_add_i32 s5, s5, 0x20400
	v_mov_b32_e32 v1, s5
	ds_read_b64 v[2:3], v1
	s_ashr_i32 s15, s11, 31
	s_mov_b32 s14, s11
	s_lshl_b64 s[10:11], s[14:15], 2
	s_waitcnt lgkmcnt(0)
	v_readfirstlane_b32 s5, v2
	v_readfirstlane_b32 s16, v3
	s_add_u32 s50, s5, s10
	s_addc_u32 s51, s16, s11
